# attention epilogue: MLA gain table staged once per workgroup in LDS (2 KB) and read with ds_read_b128 instead of 8 global loads per unit
# speedup vs baseline: 1.0107x; 1.0107x over previous
; __device__ __forceinline__ unsigned xb_add(unsigned* p, unsigned v) { return __hip_atomic_fetch_add(p, v, __ATOMIC_RELAXED, __HIP_MEMORY_SCOPE_AGENT); }
; DI void attn_unit(int b, int h, int qb, const bf16* Qb, const bf16* Kb, const bf16* Vt, const int* positions, bf16* O, LAS unsigned char* lds, int tid) {
;     const int wave = __builtin_amdgcn_readfirstlane(tid >> 6), lane = tid & 63, r32 = lane & 31, hi = lane >> 5;
;     const int rowbase = b * T, q0 = qb * 256, qrow = q0 + 32 * wave + r32;
;     const int kkey0 = tid / 12, kc0 = tid % 12, vd = tid >> 3, vc = tid & 7;
;     const bf16* kg0 = Kb + (size_t)(rowbase + kkey0) * 768 + h * 96 + kc0 * 8;
;     const bf16* vg = Vt + (size_t)(h * 64 + vd) * VT_LD + rowbase + vc * 8;
;     const int NT = (q0 + 256) / 64, NTF = q0 / 64;
;     const int kp1 = tid < 256 ? 512 + tid : tid;
;     const int kkey1 = kp1 / 12, kc1 = kp1 % 12;
;     const bf16* kg1 = Kb + (size_t)(rowbase + kkey1) * 768 + h * 96 + kc1 * 8;
; __global__ void __launch_bounds__(512, 2) mk_fwd(Args a) {
;     ...
;         if (tid == 0) *qslot = ticket;
;         __syncthreads();
;         int q = *qslot;
;         __syncthreads();
;         while (q < per_q) {
;             if (tid == 0) ticket = (int)xb_add(&barw[XB_QHEAD(xq)], 1u);
;             const int bh = NQ == 8 ? xq * 8 + (q & 7) : (q & 63), qb = NQ == 8 ? 15 - (q >> 3) : 15 - (q >> 6);
.LBB0_836:
	s_or_b64 exec, exec, s[2:3]
	s_and_saveexec_b64 s[2:3], s[0:1]
	s_add_i32 s12, 0, 0x24fe0
	v_mov_b32_e32 v0, s12
	ds_write_b32 v0, v200
	s_or_b64 exec, exec, s[2:3]
	v_lshlrev_b32_e32 v254, 2, v197
	global_load_dword v255, v254, s[86:87]
	s_waitcnt vmcnt(0)
	v_add_u32_e32 v254, 0x20000, v254
	ds_write_b32 v254, v255
	s_movk_i32 s12, 0x80
	s_and_b64 s[2:3], s[8:9], exec
	s_cselect_b32 s17, s12, 0x400
	s_add_i32 s24, 0, 0x24fe0
	v_mov_b32_e32 v0, s24
	s_waitcnt vmcnt(0) lgkmcnt(0)
	s_barrier
	ds_read_b32 v0, v0
	s_mov_b32 s13, 0
	s_waitcnt lgkmcnt(0)
	s_barrier
	v_cmp_le_i32_e32 vcc, s17, v0
	v_readfirstlane_b32 s12, v0
	s_cbranch_vccnz .LBB0_871
	s_lshl_b32 s25, s16, 3
	s_and_b64 s[2:3], s[8:9], exec
	s_movk_i32 s2, 0x100
	v_bfe_u32 v3, v197, 5, 1
	v_cmp_gt_u32_e32 vcc, s2, v197
	s_movk_i32 s2, 0x88
	v_mad_u32_u24 v204, v198, s2, 0
	v_mov_b32_e32 v8, 0x3f847ae1
	v_mov_b32_e32 v9, 0x3ff00000
	v_cmp_eq_u32_e64 s[2:3], 0, v3
	v_add_u32_e32 v2, 0x200, v197
	v_mul_u32_u24_e32 v0, 0x1556, v197
	v_cndmask_b32_e64 v165, v8, v9, s[2:3]
	v_mov_b32_e32 v8, 0x47ae147b
	v_cndmask_b32_e64 v164, v8, 0, s[2:3]
	v_mov_b32_e32 v8, 0x3f770893
	v_mov_b32_e32 v9, 0x3fe1feb3
	v_cndmask_b32_e64 v167, v8, v9, s[2:3]
	v_mov_b32_e32 v8, 0x80241edf
	v_mov_b32_e32 v9, 0x3c1c381e
	v_cndmask_b32_e64 v166, v8, v9, s[2:3]
	v_mov_b32_e32 v8, 0x3f69e7c6
	v_mov_b32_e32 v9, 0x3fd43d13
	v_cndmask_b32_e64 v169, v8, v9, s[2:3]
	v_mov_b32_e32 v8, 0xe43390b7
	v_mov_b32_e32 v9, 0x6248490f
	v_cndmask_b32_e64 v168, v8, v9, s[2:3]
	v_mov_b32_e32 v8, 0x3f5d22a4
	v_mov_b32_e32 v9, 0x3fc6c310
	v_cndmask_b32_e64 v171, v8, v9, s[2:3]
	v_mov_b32_e32 v8, 0xfa316fad
	v_mov_b32_e32 v9, 0xe3769f3f
	v_cndmask_b32_e64 v170, v8, v9, s[2:3]
	v_mov_b32_e32 v8, 0x3f50624d
	v_mov_b32_e32 v9, 0x3fb99999
	v_cndmask_b32_e64 v173, v8, v9, s[2:3]
	v_mov_b32_e32 v8, 0xd2f1a9fc
	v_mov_b32_e32 v9, 0x9999999a
	v_cndmask_b32_e32 v2, v197, v2, vcc
	v_cndmask_b32_e64 v172, v8, v9, s[2:3]
	v_mov_b32_e32 v8, 0x3f426d42
	v_mov_b32_e32 v9, 0x3faccab8
	v_lshrrev_b32_e32 v202, 16, v0
	v_mul_u32_u24_e32 v5, 0x1556, v2
	v_cndmask_b32_e64 v175, v8, v9, s[2:3]
	v_mov_b32_e32 v8, 0xcce9b24c
	v_mov_b32_e32 v9, 0x602d2697
	v_and_b32_e32 v201, 31, v197
	v_mul_lo_u16_e32 v0, 12, v202
	v_lshrrev_b32_e32 v203, 16, v5
	s_movk_i32 s14, 0xd0
	v_cndmask_b32_e64 v174, v8, v9, s[2:3]
	v_mov_b32_e32 v8, 0x3f34b96b
	v_mov_b32_e32 v9, 0x3fa030dc
	v_sub_u16_e32 v4, v197, v0
	v_mov_b32_e32 v1, 0
	v_mul_lo_u16_e32 v5, 12, v203
	v_mad_u32_u24 v6, v202, s14, 0
	v_mad_u32_u24 v7, v203, s14, 0
	v_cndmask_b32_e64 v177, v8, v9, s[2:3]
	v_mov_b32_e32 v8, 0xe9c2da2c
	v_mov_b32_e32 v9, 0x4ea03a73
	v_mad_u32_u24 v206, v201, s14, 0
	v_readlane_b32 s14, v253, 45
	v_lshlrev_b32_e32 v0, 3, v4
	v_sub_u16_e32 v5, v2, v5
	v_lshlrev_b32_e32 v160, 4, v3
	v_mov_b32_e32 v161, v1
	v_cndmask_b32_e64 v176, v8, v9, s[2:3]
	v_mov_b32_e32 v8, 0x3f274eea
	v_mov_b32_e32 v9, 0x3f9235a7
	v_readlane_b32 s15, v253, 46
	v_readlane_b32 s20, v253, 51
	v_lshlrev_b32_e32 v2, 3, v5
	v_lshlrev_b32_e32 v4, 4, v4
	v_lshlrev_b32_e32 v5, 4, v5
	v_cndmask_b32_e64 v179, v8, v9, s[2:3]
	v_mov_b32_e32 v8, 0x61c12624
	v_mov_b32_e32 v9, 0x1c5ee5cc
	v_lshl_add_u64 v[180:181], s[14:15], 0, v[160:161]
	v_lshlrev_b32_e32 v182, 1, v0
	s_movk_i32 s18, 0x3400
	s_mov_b32 s14, 0x6dc9c883
	v_readlane_b32 s21, v253, 52
	v_mbcnt_lo_u32_b32 v0, -1, 0
	s_cselect_b32 s26, 3, 6
	v_lshl_add_u64 v[162:163], s[84:85], 0, v[160:161]
	v_cndmask_b32_e64 v178, v8, v9, s[2:3]
	v_lshl_add_u32 v205, v3, 3, 0
	v_lshlrev_b32_e32 v207, 2, v3
	v_mul_u32_u24_e32 v208, 0x88, v201
	s_movk_i32 s27, 0x600
	v_mov_b32_e32 v183, v1
	v_lshlrev_b32_e32 v184, 1, v2
	s_mov_b32 s15, 0x3fc45f30
	s_mov_b32 s16, 0x3e16c740
	s_mov_b32 s28, 0x48000
	s_mov_b32 s29, 0x8a00
	s_mov_b32 s30, 0x40c00000
	s_mov_b32 s31, 0xe000
	v_mov_b64_e32 v[186:187], s[20:21]
	v_mov_b32_e32 v161, 0x18000
	v_add_u32_e32 v209, v6, v4
	v_add_u32_e32 v210, v7, v5
	v_add3_u32 v211, v204, v199, s18
	v_mov_b32_e32 v212, 0xff800000
	v_mbcnt_hi_u32_b32 v213, -1, v0
	s_branch .LBB0_841

; DI unsigned pk2(float lo, float hi) { f32x2_t v = {lo, hi}; bf16x2_t b = __builtin_convertvector(v, bf16x2_t); return __builtin_bit_cast(unsigned, b); }
; DI float bflo(unsigned u) { return __uint_as_float(u << 16); }
; DI float bfhi(unsigned u) { return __uint_as_float(u & 0xffff0000u); }
; template <int NR> DI void mla_norm_rows(bf16* A, const float* g_mla, int m0, int mstride, int lane) {
;     ...
;         const u32x4 a = am[r];
;         float v[8] = {bflo(a.x), bfhi(a.x), bflo(a.y), bfhi(a.y), bflo(a.z), bfhi(a.z), bflo(a.w), bfhi(a.w)};
;         float s2 = 0.f;
; #pragma unroll
;         for (int i = 0; i < 8; ++i) s2 += v[i] * v[i];
;         const float rr = rsqrtf(wave_sum(s2) * (1.f / 512.f) + EPS);
;         u32x4 w; w.x = pk2(v[0] * rr * gm[0], v[1] * rr * gm[1]); w.y = pk2(v[2] * rr * gm[2], v[3] * rr * gm[3]); w.z = pk2(v[4] * rr * gm[4], v[5] * rr * gm[5]); w.w = pk2(v[6] * rr * gm[6], v[7] * rr * gm[7]);
;         *(u32x4*)(A + (size_t)(m0 + r * mstride) * 1024 + 8 * lane) = w;
; DI void attn_unit(int b, int h, int qb, const bf16* Qb, const bf16* Kb, const bf16* Vt, const int* positions, bf16* O, LAS unsigned char* lds, int tid) {
;     ...
;     lrun += __shfl_xor(lrun, 32);
;     const float inv = 1.0f / lrun;
;     bf16* op = O + (size_t)(rowbase + qrow) * 1024 + h * 64;
; #pragma unroll
;     for (int blk = 0; blk < 2; ++blk)
; #pragma unroll
;         for (int gp = 0; gp < 2; ++gp) {
;             unsigned e0, e1, o0w, o1w;
;             if (blk == 0) { e0 = pk2(o0[8 * gp] * inv, o0[8 * gp + 1] * inv); e1 = pk2(o0[8 * gp + 2] * inv, o0[8 * gp + 3] * inv); o0w = pk2(o0[8 * gp + 4] * inv, o0[8 * gp + 5] * inv); o1w = pk2(o0[8 * gp + 6] * inv, o0[8 * gp + 7] * inv); }
;             else { e0 = pk2(o1[8 * gp] * inv, o1[8 * gp + 1] * inv); e1 = pk2(o1[8 * gp + 2] * inv, o1[8 * gp + 3] * inv); o0w = pk2(o1[8 * gp + 4] * inv, o1[8 * gp + 5] * inv); o1w = pk2(o1[8 * gp + 6] * inv, o1[8 * gp + 7] * inv); }
;             const unsigned send0 = hi ? e0 : o0w, send1 = hi ? e1 : o1w;
;             const unsigned recv0 = (unsigned)__shfl_xor((int)send0, 32), recv1 = (unsigned)__shfl_xor((int)send1, 32);
;             u32x4 w;
;             if (hi == 0) { w.x = e0; w.y = e1; w.z = recv0; w.w = recv1; }
;             else { w.x = recv0; w.y = recv1; w.z = o0w; w.w = o1w; }
;             *(u32x4*)(op + 32 * blk + 16 * gp + 8 * hi) = w;
;         }
.LBB0_869:
	v_and_b32_e32 v2, 64, v213
	v_xor_b32_e32 v0, 32, v213
	v_add_u32_e32 v2, 64, v2
	v_cmp_lt_i32_e32 vcc, v0, v2
	s_lshl_b32 s12, s18, 1
	v_lshl_add_u64 v[2:3], v[180:181], 0, s[12:13]
	v_cndmask_b32_e32 v0, v213, v0, vcc
	v_lshlrev_b32_e32 v14, 2, v0
	ds_bpermute_b32 v0, v14, v48
	s_waitcnt lgkmcnt(0)
	s_barrier
	v_add_f32_e32 v0, v48, v0
	v_div_scale_f32 v4, s[18:19], v0, v0, 1.0
	v_rcp_f32_e32 v5, v4
	s_nop 0
	v_fma_f32 v6, -v4, v5, 1.0
	v_fmac_f32_e32 v5, v6, v5
	v_div_scale_f32 v6, vcc, 1.0, v0, 1.0
	v_mul_f32_e32 v7, v6, v5
	v_fma_f32 v8, -v4, v7, v6
	v_fmac_f32_e32 v7, v8, v5
	v_fma_f32 v4, -v4, v7, v6
	v_div_fmas_f32 v4, v4, v5, v7
	v_div_fixup_f32 v0, v4, v0, 1.0
	s_waitcnt vmcnt(0)
	v_and_b32_e32 v95, 32, v213
	v_lshrrev_b32_e32 v95, 1, v95
	s_lshl_b32 s98, s12, 1
	v_add_u32_e32 v95, s98, v95
	v_add_u32_e32 v95, 0x20000, v95
	ds_read_b128 v[100:103], v95
	ds_read_b128 v[104:107], v95 offset:32
	ds_read_b128 v[108:111], v95 offset:64
	ds_read_b128 v[112:115], v95 offset:96
	ds_read_b128 v[116:119], v95 offset:128
	ds_read_b128 v[120:123], v95 offset:160
	ds_read_b128 v[124:127], v95 offset:192
	ds_read_b128 v[128:131], v95 offset:224
	v_pk_mul_f32 v[96:97], v[32:33], v[32:33]
	v_pk_fma_f32 v[96:97], v[34:35], v[34:35], v[96:97]
	v_pk_fma_f32 v[96:97], v[36:37], v[36:37], v[96:97]
	v_pk_fma_f32 v[96:97], v[38:39], v[38:39], v[96:97]
	v_pk_fma_f32 v[96:97], v[40:41], v[40:41], v[96:97]
	v_pk_fma_f32 v[96:97], v[42:43], v[42:43], v[96:97]
	v_pk_fma_f32 v[96:97], v[44:45], v[44:45], v[96:97]
	v_pk_fma_f32 v[96:97], v[46:47], v[46:47], v[96:97]
	v_pk_fma_f32 v[96:97], v[16:17], v[16:17], v[96:97]
	v_pk_fma_f32 v[96:97], v[18:19], v[18:19], v[96:97]
	v_pk_fma_f32 v[96:97], v[20:21], v[20:21], v[96:97]
	v_pk_fma_f32 v[96:97], v[22:23], v[22:23], v[96:97]
	v_pk_fma_f32 v[96:97], v[24:25], v[24:25], v[96:97]
	v_pk_fma_f32 v[96:97], v[26:27], v[26:27], v[96:97]
	v_pk_fma_f32 v[96:97], v[28:29], v[28:29], v[96:97]
	v_pk_fma_f32 v[96:97], v[30:31], v[30:31], v[96:97]
	v_add_f32_e32 v96, v96, v97
	v_mul_f32_e32 v97, v0, v0
	v_mul_f32_e32 v96, v96, v97
	ds_bpermute_b32 v97, v14, v96
	s_waitcnt lgkmcnt(0)
	v_pk_mul_f32 v[32:33], v[32:33], v[100:101]
	v_pk_mul_f32 v[34:35], v[34:35], v[102:103]
	v_pk_mul_f32 v[36:37], v[36:37], v[104:105]
	v_pk_mul_f32 v[38:39], v[38:39], v[106:107]
	v_pk_mul_f32 v[40:41], v[40:41], v[108:109]
	v_pk_mul_f32 v[42:43], v[42:43], v[110:111]
	v_pk_mul_f32 v[44:45], v[44:45], v[112:113]
	v_pk_mul_f32 v[46:47], v[46:47], v[114:115]
	v_pk_mul_f32 v[16:17], v[16:17], v[116:117]
	v_pk_mul_f32 v[18:19], v[18:19], v[118:119]
	v_pk_mul_f32 v[20:21], v[20:21], v[120:121]
	v_pk_mul_f32 v[22:23], v[22:23], v[122:123]
	v_pk_mul_f32 v[24:25], v[24:25], v[124:125]
	v_pk_mul_f32 v[26:27], v[26:27], v[126:127]
	v_pk_mul_f32 v[28:29], v[28:29], v[128:129]
	v_pk_mul_f32 v[30:31], v[30:31], v[130:131]
	s_waitcnt lgkmcnt(0)
	v_add_f32_e32 v96, v96, v97
	v_lshlrev_b32_e32 v94, 5, v188
	s_lshr_b32 s98, s12, 5
	v_add_u32_e32 v94, s98, v94
	s_add_u32 s98, s64, 0x13bec000
	s_addc_u32 s99, s65, 0
	s_mov_b64 s[100:101], exec
	s_mov_b32 exec_lo, -1
	s_mov_b32 exec_hi, 0
	global_store_dword v94, v96, s[98:99]
	s_mov_b64 exec, s[100:101]
	v_pk_mul_f32 v[4:5], v[38:39], v[0:1] op_sel_hi:[1,0]
	v_pk_mul_f32 v[6:7], v[36:37], v[0:1] op_sel_hi:[1,0]
	v_pk_mul_f32 v[8:9], v[34:35], v[0:1] op_sel_hi:[1,0]
	v_pk_mul_f32 v[10:11], v[32:33], v[0:1] op_sel_hi:[1,0]
	v_cvt_pk_bf16_f32 v12, v4, v5
	v_cvt_pk_bf16_f32 v13, v6, v7
	v_cvt_pk_bf16_f32 v15, v8, v9
	v_cvt_pk_bf16_f32 v32, v10, v11
	v_cndmask_b32_e64 v4, v32, v13, s[2:3]
	v_cndmask_b32_e64 v5, v15, v12, s[2:3]
	ds_bpermute_b32 v33, v14, v5
	ds_bpermute_b32 v34, v14, v4
	v_lshlrev_b64 v[4:5], 11, v[188:189]
	v_lshl_add_u64 v[6:7], v[2:3], 0, v[4:5]
	v_pk_mul_f32 v[8:9], v[44:45], v[0:1] op_sel_hi:[1,0]
	s_waitcnt lgkmcnt(1)
	v_cndmask_b32_e64 v5, v12, v33, s[2:3]
	s_waitcnt lgkmcnt(0)
	v_cndmask_b32_e64 v4, v13, v34, s[2:3]
	v_pk_mul_f32 v[12:13], v[40:41], v[0:1] op_sel_hi:[1,0]
	v_pk_mul_f32 v[2:3], v[46:47], v[0:1] op_sel_hi:[1,0]
	v_cvt_pk_bf16_f32 v8, v8, v9
	v_cvt_pk_bf16_f32 v37, v12, v13
	v_cvt_pk_bf16_f32 v35, v2, v3
	v_cndmask_b32_e64 v2, v37, v8, s[2:3]
	ds_bpermute_b32 v39, v14, v2
	v_pk_mul_f32 v[10:11], v[42:43], v[0:1] op_sel_hi:[1,0]
	v_cndmask_b32_e64 v2, v34, v32, s[2:3]
	v_cvt_pk_bf16_f32 v36, v10, v11
	v_cndmask_b32_e64 v3, v36, v35, s[2:3]
	ds_bpermute_b32 v38, v14, v3
	v_cndmask_b32_e64 v3, v33, v15, s[2:3]
	global_store_dwordx4 v[6:7], v[2:5], off
	v_pk_mul_f32 v[12:13], v[16:17], v[0:1] op_sel_hi:[1,0]
	v_pk_mul_f32 v[10:11], v[18:19], v[0:1] op_sel_hi:[1,0]
	s_waitcnt lgkmcnt(1)
	v_cndmask_b32_e64 v4, v8, v39, s[2:3]
	v_pk_mul_f32 v[8:9], v[20:21], v[0:1] op_sel_hi:[1,0]
	v_pk_mul_f32 v[2:3], v[22:23], v[0:1] op_sel_hi:[1,0]
	v_cvt_pk_bf16_f32 v8, v8, v9
	v_cvt_pk_bf16_f32 v17, v12, v13
	v_cvt_pk_bf16_f32 v15, v2, v3
	v_cndmask_b32_e64 v2, v17, v8, s[2:3]
	ds_bpermute_b32 v19, v14, v2
	v_cvt_pk_bf16_f32 v16, v10, v11
	v_cndmask_b32_e64 v3, v16, v15, s[2:3]
	s_waitcnt lgkmcnt(1)
	v_cndmask_b32_e64 v5, v35, v38, s[2:3]
	ds_bpermute_b32 v18, v14, v3
	v_cndmask_b32_e64 v3, v38, v36, s[2:3]
	v_cndmask_b32_e64 v2, v39, v37, s[2:3]
	global_store_dwordx4 v[6:7], v[2:5], off offset:32
	v_pk_mul_f32 v[10:11], v[26:27], v[0:1] op_sel_hi:[1,0]
	v_pk_mul_f32 v[12:13], v[24:25], v[0:1] op_sel_hi:[1,0]
	s_waitcnt lgkmcnt(1)
	v_cndmask_b32_e64 v4, v8, v19, s[2:3]
	v_pk_mul_f32 v[2:3], v[30:31], v[0:1] op_sel_hi:[1,0]
	v_pk_mul_f32 v[8:9], v[28:29], v[0:1] op_sel_hi:[1,0]
	v_cvt_pk_bf16_f32 v0, v2, v3
	v_cvt_pk_bf16_f32 v8, v8, v9
	v_cvt_pk_bf16_f32 v9, v10, v11
	v_cvt_pk_bf16_f32 v10, v12, v13
	v_cndmask_b32_e64 v2, v10, v8, s[2:3]
	v_cndmask_b32_e64 v3, v9, v0, s[2:3]
	ds_bpermute_b32 v11, v14, v3
	ds_bpermute_b32 v12, v14, v2
	s_waitcnt lgkmcnt(2)
	v_cndmask_b32_e64 v5, v15, v18, s[2:3]
	v_cndmask_b32_e64 v3, v18, v16, s[2:3]
	v_cndmask_b32_e64 v2, v19, v17, s[2:3]
	global_store_dwordx4 v[6:7], v[2:5], off offset:64
	s_waitcnt lgkmcnt(1)
	s_nop 0
	v_cndmask_b32_e64 v5, v0, v11, s[2:3]
	s_waitcnt lgkmcnt(0)
	v_cndmask_b32_e64 v4, v8, v12, s[2:3]
	v_cndmask_b32_e64 v3, v11, v9, s[2:3]
	v_cndmask_b32_e64 v2, v12, v10, s[2:3]
	global_store_dwordx4 v[6:7], v[2:5], off offset:96
	s_and_saveexec_b64 s[18:19], s[0:1]
	s_cbranch_execz .LBB0_840
	v_mov_b32_e32 v0, s24
	ds_write_b32 v0, v200
	s_branch .LBB0_840

; __global__ void __launch_bounds__(512, 2) mk_fwd(Args a) {
;     extern __shared__ __attribute__((aligned(16))) unsigned char lds_raw[];
	.amdhsa_kernel _Z6mk_fwd4Args
		.amdhsa_group_segment_fixed_size 0
		.amdhsa_private_segment_fixed_size 0
		.amdhsa_kernarg_size 480
		.amdhsa_user_sgpr_count 2
		.amdhsa_user_sgpr_dispatch_ptr 0
		.amdhsa_user_sgpr_queue_ptr 0
		.amdhsa_user_sgpr_kernarg_segment_ptr 1
		.amdhsa_user_sgpr_dispatch_id 0
		.amdhsa_user_sgpr_kernarg_preload_length 0
		.amdhsa_user_sgpr_kernarg_preload_offset 0
		.amdhsa_user_sgpr_private_segment_size 0
		.amdhsa_uses_dynamic_stack 0
		.amdhsa_enable_private_segment 0
		.amdhsa_system_sgpr_workgroup_id_x 1
		.amdhsa_system_sgpr_workgroup_id_y 0
		.amdhsa_system_sgpr_workgroup_id_z 0
		.amdhsa_system_sgpr_workgroup_info 0
		.amdhsa_system_vgpr_workitem_id 2
		.amdhsa_next_free_vgpr 256
		.amdhsa_next_free_sgpr 102
		.amdhsa_accum_offset 256
		.amdhsa_reserve_vcc 1
		.amdhsa_float_round_mode_32 0
		.amdhsa_float_round_mode_16_64 0
		.amdhsa_float_denorm_mode_32 3
		.amdhsa_float_denorm_mode_16_64 3
		.amdhsa_dx10_clamp 1
		.amdhsa_ieee_mode 1
		.amdhsa_fp16_overflow 0
		.amdhsa_tg_split 0
		.amdhsa_exception_fp_ieee_invalid_op 0
		.amdhsa_exception_fp_denorm_src 0
		.amdhsa_exception_fp_ieee_div_zero 0
		.amdhsa_exception_fp_ieee_overflow 0
		.amdhsa_exception_fp_ieee_underflow 0
		.amdhsa_exception_fp_ieee_inexact 0
		.amdhsa_exception_int_div_zero 0
	.end_amdhsa_kernel

; __global__ void __launch_bounds__(512, 2) mk_fwd(Args a) {
;     extern __shared__ __attribute__((aligned(16))) unsigned char lds_raw[];
amdhsa.kernels:
  - .agpr_count:     0
    .args:
      - .offset:         0
        .size:           224
        .value_kind:     by_value
      - .offset:         224
        .size:           4
        .value_kind:     hidden_block_count_x
      - .offset:         228
        .size:           4
        .value_kind:     hidden_block_count_y
      - .offset:         232
        .size:           4
        .value_kind:     hidden_block_count_z
      - .offset:         236
        .size:           2
        .value_kind:     hidden_group_size_x
      - .offset:         238
        .size:           2
        .value_kind:     hidden_group_size_y
      - .offset:         240
        .size:           2
        .value_kind:     hidden_group_size_z
      - .offset:         242
        .size:           2
        .value_kind:     hidden_remainder_x
      - .offset:         244
        .size:           2
        .value_kind:     hidden_remainder_y
      - .offset:         246
        .size:           2
        .value_kind:     hidden_remainder_z
      - .offset:         264
        .size:           8
        .value_kind:     hidden_global_offset_x
      - .offset:         272
        .size:           8
        .value_kind:     hidden_global_offset_y
      - .offset:         280
        .size:           8
        .value_kind:     hidden_global_offset_z
      - .offset:         288
        .size:           2
        .value_kind:     hidden_grid_dims
      - .offset:         312
        .size:           8
        .value_kind:     hidden_multigrid_sync_arg
      - .offset:         344
        .size:           4
        .value_kind:     hidden_dynamic_lds_size
    .group_segment_fixed_size: 0
    .kernarg_segment_align: 8
    .kernarg_segment_size: 480
    .language:       OpenCL C
    .language_version:
      - 2
      - 0
    .max_flat_workgroup_size: 512
    .name:           _Z6mk_fwd4Args
    .private_segment_fixed_size: 0
    .sgpr_count:     108
    .sgpr_spill_count: 75
    .symbol:         _Z6mk_fwd4Args.kd
    .uniform_work_group_size: 1
    .uses_dynamic_stack: false
    .vgpr_count:     256
    .vgpr_spill_count: 0
    .wavefront_size: 64
